# hgrn_scan dead address code removed; attention v_pk_add_f32 split to scalar adds
# speedup vs baseline: 1.0081x; 1.0023x over previous
.LBB0_492:
	s_waitcnt vmcnt(16)
	v_lshl_add_u64 v[26:27], v[2:3], 0, s[60:61]
	v_mov_b32_e32 v168, v26
	v_cmp_gt_u64_e64 s[2:3], s[54:55], v[26:27]
	v_add_co_u32_e32 v10, vcc, s11, v8
	s_nop 0
	s_nop 0
	v_addc_co_u32_e32 v11, vcc, -1, v9, vcc
	v_add_co_u32_e32 v30, vcc, s16, v6
	s_nop 1
	v_addc_co_u32_e32 v31, vcc, -1, v7, vcc
	v_add_co_u32_e32 v12, vcc, s17, v8
	s_nop 0
	s_nop 0
	v_addc_co_u32_e32 v13, vcc, -1, v9, vcc
	v_add_co_u32_e32 v14, vcc, s18, v8
	s_nop 1
	v_addc_co_u32_e32 v15, vcc, -1, v9, vcc
	v_add_co_u32_e32 v18, vcc, s19, v8
	s_nop 0
	s_nop 0
	v_addc_co_u32_e32 v19, vcc, -1, v9, vcc
	v_mov_b32_e32 v0, v132
	v_mov_b32_e32 v111, v133
	v_mov_b32_e32 v113, v134
	v_mov_b32_e32 v115, v135
	v_add_co_u32_e32 v20, vcc, s20, v8
	s_nop 1
	v_addc_co_u32_e32 v21, vcc, -1, v9, vcc
	v_add_co_u32_e32 v22, vcc, s21, v8
	s_nop 0
	s_nop 0
	v_addc_co_u32_e32 v23, vcc, -1, v9, vcc
	v_add_co_u32_e32 v24, vcc, s22, v8
	s_nop 1
	v_addc_co_u32_e32 v25, vcc, -1, v9, vcc
	v_mov_b32_e32 v117, v136
	v_mov_b32_e32 v118, v137
	v_mov_b32_e32 v119, v138
	v_add_co_u32_e32 v30, vcc, s23, v8
	s_nop 0
	s_nop 0
	v_addc_co_u32_e32 v31, vcc, -1, v9, vcc
	v_add_co_u32_e32 v34, vcc, s24, v8
	v_mov_b32_e32 v120, v139
	s_nop 0
	v_addc_co_u32_e32 v35, vcc, -1, v9, vcc
	v_add_co_u32_e32 v70, vcc, s25, v8
	v_mov_b32_e32 v121, v140
	s_nop 0
	v_addc_co_u32_e32 v71, vcc, -1, v9, vcc
	v_add_co_u32_e32 v74, vcc, s26, v8
	v_mov_b32_e32 v122, v141
	s_nop 0
	v_addc_co_u32_e32 v75, vcc, -1, v9, vcc
	v_add_co_u32_e32 v86, vcc, s27, v8
	s_nop 0
	s_nop 0
	v_addc_co_u32_e32 v87, vcc, -1, v9, vcc
	v_add_co_u32_e32 v90, vcc, s28, v8
	v_mov_b32_e32 v123, v142
	s_nop 0
	v_addc_co_u32_e32 v91, vcc, -1, v9, vcc
	v_add_co_u32_e32 v94, vcc, s29, v8
	s_nop 1
	v_addc_co_u32_e32 v95, vcc, -1, v9, vcc
	v_mov_b32_e32 v124, v143
	v_mov_b32_e32 v125, v144
	v_mov_b32_e32 v126, v145
	v_add_co_u32_e32 v96, vcc, s30, v8
	s_nop 1
	v_addc_co_u32_e32 v97, vcc, -1, v9, vcc
	v_lshl_add_u64 v[26:27], v[26:27], 0, 16
	v_cmp_gt_u64_e32 vcc, s[54:55], v[26:27]
	v_mov_b32_e32 v127, v146
	s_nop 0
	s_nop 0
	v_mov_b32_e32 v128, v147
	v_lshlrev_b32_e32 v108, 16, v0
	v_add_u32_e32 v162, v168, v150
	v_add_u32_e32 v162, 17, v162
	v_min_u32_e32 v162, 0x7ff, v162
	v_lshlrev_b32_e32 v162, 9, v162
	v_mov_b32_e32 v163, 0
	v_lshl_add_u64 v[164:165], v[4:5], 0, v[162:163]
	v_lshl_add_u64 v[166:167], v[6:7], 0, v[154:155]
	v_lshl_add_u64 v[166:167], v[166:167], 0, s[56:57]
	ds_bpermute_b32 v40, v156, v158 offset:0
	ds_bpermute_b32 v41, v156, v159 offset:0
	ds_bpermute_b32 v28, v156, v160 offset:0
	ds_bpermute_b32 v29, v156, v161 offset:0
	ds_bpermute_b32 v42, v156, v158 offset:16
	ds_bpermute_b32 v43, v156, v159 offset:16
	ds_bpermute_b32 v32, v156, v160 offset:16
	ds_bpermute_b32 v33, v156, v161 offset:16
	ds_bpermute_b32 v44, v156, v158 offset:32
	ds_bpermute_b32 v45, v156, v159 offset:32
	ds_bpermute_b32 v38, v156, v160 offset:32
	ds_bpermute_b32 v39, v156, v161 offset:32
	ds_bpermute_b32 v46, v156, v158 offset:48
	ds_bpermute_b32 v47, v156, v159 offset:48
	ds_bpermute_b32 v48, v156, v160 offset:48
	ds_bpermute_b32 v49, v156, v161 offset:48
	ds_bpermute_b32 v56, v156, v158 offset:64
	ds_bpermute_b32 v57, v156, v159 offset:64
	ds_bpermute_b32 v50, v156, v160 offset:64
	ds_bpermute_b32 v51, v156, v161 offset:64
	ds_bpermute_b32 v58, v156, v158 offset:80
	ds_bpermute_b32 v59, v156, v159 offset:80
	ds_bpermute_b32 v52, v156, v160 offset:80
	ds_bpermute_b32 v53, v156, v161 offset:80
	ds_bpermute_b32 v60, v156, v158 offset:96
	ds_bpermute_b32 v61, v156, v159 offset:96
	ds_bpermute_b32 v54, v156, v160 offset:96
	ds_bpermute_b32 v55, v156, v161 offset:96
	ds_bpermute_b32 v76, v156, v158 offset:112
	ds_bpermute_b32 v77, v156, v159 offset:112
	ds_bpermute_b32 v64, v156, v160 offset:112
	ds_bpermute_b32 v65, v156, v161 offset:112
	ds_bpermute_b32 v78, v156, v158 offset:128
	ds_bpermute_b32 v79, v156, v159 offset:128
	ds_bpermute_b32 v62, v156, v160 offset:128
	ds_bpermute_b32 v63, v156, v161 offset:128
	ds_bpermute_b32 v80, v156, v158 offset:144
	ds_bpermute_b32 v81, v156, v159 offset:144
	ds_bpermute_b32 v66, v156, v160 offset:144
	ds_bpermute_b32 v67, v156, v161 offset:144
	ds_bpermute_b32 v82, v156, v158 offset:160
	ds_bpermute_b32 v83, v156, v159 offset:160
	ds_bpermute_b32 v68, v156, v160 offset:160
	ds_bpermute_b32 v69, v156, v161 offset:160
	ds_bpermute_b32 v100, v156, v158 offset:176
	ds_bpermute_b32 v101, v156, v159 offset:176
	ds_bpermute_b32 v72, v156, v160 offset:176
	ds_bpermute_b32 v73, v156, v161 offset:176
	ds_bpermute_b32 v102, v156, v158 offset:192
	ds_bpermute_b32 v103, v156, v159 offset:192
	ds_bpermute_b32 v84, v156, v160 offset:192
	ds_bpermute_b32 v85, v156, v161 offset:192
	ds_bpermute_b32 v104, v156, v158 offset:208
	ds_bpermute_b32 v105, v156, v159 offset:208
	ds_bpermute_b32 v88, v156, v160 offset:208
	ds_bpermute_b32 v89, v156, v161 offset:208
	ds_bpermute_b32 v106, v156, v158 offset:224
	ds_bpermute_b32 v107, v156, v159 offset:224
	ds_bpermute_b32 v92, v156, v160 offset:224
	ds_bpermute_b32 v93, v156, v161 offset:224
	ds_bpermute_b32 v98, v156, v158 offset:240
	ds_bpermute_b32 v99, v156, v159 offset:240
	ds_bpermute_b32 v26, v156, v160 offset:240
	ds_bpermute_b32 v27, v156, v161 offset:240
	global_load_dwordx2 v[160:161], v[164:165], off
	global_load_dwordx2 v[158:159], v[166:167], off
	v_lshl_add_u64 v[148:149], v[10:11], 0, s[58:59]
	global_load_dword v132, v[148:149], off
	v_lshl_add_u64 v[148:149], v[12:13], 0, s[58:59]
	global_load_dword v133, v[148:149], off
	v_lshl_add_u64 v[148:149], v[14:15], 0, s[58:59]
	global_load_dword v134, v[148:149], off
	v_lshl_add_u64 v[148:149], v[18:19], 0, s[58:59]
	global_load_dword v135, v[148:149], off
	v_lshl_add_u64 v[148:149], v[20:21], 0, s[58:59]
	global_load_dword v136, v[148:149], off
	v_lshl_add_u64 v[148:149], v[22:23], 0, s[58:59]
	global_load_dword v137, v[148:149], off
	v_lshl_add_u64 v[148:149], v[24:25], 0, s[58:59]
	global_load_dword v138, v[148:149], off
	v_lshl_add_u64 v[148:149], v[30:31], 0, s[58:59]
	global_load_dword v139, v[148:149], off
	v_lshl_add_u64 v[148:149], v[34:35], 0, s[58:59]
	global_load_dword v140, v[148:149], off
	v_lshl_add_u64 v[148:149], v[70:71], 0, s[58:59]
	global_load_dword v141, v[148:149], off
	v_lshl_add_u64 v[148:149], v[74:75], 0, s[58:59]
	global_load_dword v142, v[148:149], off
	v_lshl_add_u64 v[148:149], v[86:87], 0, s[58:59]
	global_load_dword v143, v[148:149], off
	v_lshl_add_u64 v[148:149], v[90:91], 0, s[58:59]
	global_load_dword v144, v[148:149], off
	v_lshl_add_u64 v[148:149], v[94:95], 0, s[58:59]
	global_load_dword v145, v[148:149], off
	v_lshl_add_u64 v[148:149], v[96:97], 0, s[58:59]
	global_load_dword v146, v[148:149], off
	v_lshl_add_u64 v[148:149], v[8:9], 0, s[58:59]
	global_load_dword v147, v[148:149], off
	s_waitcnt lgkmcnt(0)
	v_and_b32_e32 v109, 0xffff0000, v0
	v_lshlrev_b32_e32 v110, 16, v111
	v_and_b32_e32 v111, 0xffff0000, v111
	v_pk_fma_f32 v[16:17], v[16:17], v[40:41], v[108:109]
	v_lshlrev_b32_e32 v112, 16, v113
	v_and_b32_e32 v113, 0xffff0000, v113
	v_pk_mul_f32 v[28:29], v[28:29], v[16:17]
	v_pk_fma_f32 v[16:17], v[16:17], v[42:43], v[110:111]
	v_lshlrev_b32_e32 v114, 16, v115
	v_and_b32_e32 v115, 0xffff0000, v115
	v_cvt_pk_bf16_f32 v0, v28, v29
	v_pk_mul_f32 v[28:29], v[32:33], v[16:17]
	v_pk_fma_f32 v[16:17], v[16:17], v[44:45], v[112:113]
	v_lshlrev_b32_e32 v116, 16, v117
	v_and_b32_e32 v117, 0xffff0000, v117
	v_cvt_pk_bf16_f32 v108, v28, v29
	v_pk_mul_f32 v[28:29], v[38:39], v[16:17]
	v_pk_fma_f32 v[16:17], v[16:17], v[46:47], v[114:115]
	v_cvt_pk_bf16_f32 v109, v28, v29
	v_pk_mul_f32 v[28:29], v[48:49], v[16:17]
	v_pk_fma_f32 v[16:17], v[16:17], v[56:57], v[116:117]
	v_cvt_pk_bf16_f32 v46, v28, v29
	v_pk_mul_f32 v[28:29], v[50:51], v[16:17]
	v_lshlrev_b32_e32 v32, 16, v119
	v_cvt_pk_bf16_f32 v47, v28, v29
	v_lshlrev_b32_e32 v28, 16, v118
	v_and_b32_e32 v29, 0xffff0000, v118
	v_and_b32_e32 v33, 0xffff0000, v119
	v_pk_fma_f32 v[16:17], v[16:17], v[58:59], v[28:29]
	v_lshlrev_b32_e32 v38, 16, v120
	v_and_b32_e32 v39, 0xffff0000, v120
	v_pk_mul_f32 v[28:29], v[52:53], v[16:17]
	v_pk_fma_f32 v[16:17], v[16:17], v[60:61], v[32:33]
	v_lshlrev_b32_e32 v40, 16, v121
	v_and_b32_e32 v41, 0xffff0000, v121
	v_cvt_pk_bf16_f32 v48, v28, v29
	v_pk_mul_f32 v[28:29], v[54:55], v[16:17]
	v_pk_fma_f32 v[16:17], v[16:17], v[76:77], v[38:39]
	v_lshlrev_b32_e32 v42, 16, v122
	v_and_b32_e32 v43, 0xffff0000, v122
	v_cvt_pk_bf16_f32 v49, v28, v29
	v_pk_mul_f32 v[28:29], v[64:65], v[16:17]
	v_pk_fma_f32 v[16:17], v[16:17], v[78:79], v[40:41]
	v_cvt_pk_bf16_f32 v50, v28, v29
	v_pk_mul_f32 v[28:29], v[62:63], v[16:17]
	v_pk_fma_f32 v[16:17], v[16:17], v[80:81], v[42:43]
	v_lshlrev_b32_e32 v44, 16, v123
	v_cvt_pk_bf16_f32 v51, v28, v29
	v_pk_mul_f32 v[28:29], v[66:67], v[16:17]
	v_and_b32_e32 v45, 0xffff0000, v123
	v_cvt_pk_bf16_f32 v52, v28, v29
	v_lshlrev_b32_e32 v28, 16, v124
	v_and_b32_e32 v29, 0xffff0000, v124
	v_pk_fma_f32 v[16:17], v[16:17], v[82:83], v[44:45]
	v_lshlrev_b32_e32 v32, 16, v125
	v_and_b32_e32 v33, 0xffff0000, v125
	v_pk_mul_f32 v[44:45], v[68:69], v[16:17]
	v_lshlrev_b32_e32 v38, 16, v126
	v_and_b32_e32 v39, 0xffff0000, v126
	v_cvt_pk_bf16_f32 v44, v44, v45
	s_add_u32 s60, s60, 16
	s_addc_u32 s61, s61, 0
	s_add_i32 s2, s60, -16
	v_lshl_add_u64 v[6:7], v[6:7], 0, s[56:57]
	s_cmpk_gt_u32 s2, 0x6f
	v_pk_fma_f32 v[16:17], v[16:17], v[100:101], v[28:29]
	s_nop 0
	v_pk_mul_f32 v[28:29], v[72:73], v[16:17]
	v_pk_fma_f32 v[16:17], v[16:17], v[102:103], v[32:33]
	v_lshlrev_b32_e32 v40, 16, v127
	v_and_b32_e32 v41, 0xffff0000, v127
	v_cvt_pk_bf16_f32 v45, v28, v29
	v_pk_mul_f32 v[28:29], v[84:85], v[16:17]
	v_pk_fma_f32 v[16:17], v[16:17], v[104:105], v[38:39]
	v_lshlrev_b32_e32 v42, 16, v128
	v_and_b32_e32 v43, 0xffff0000, v128
	v_cvt_pk_bf16_f32 v32, v28, v29
	v_pk_mul_f32 v[28:29], v[88:89], v[16:17]
	v_pk_fma_f32 v[16:17], v[16:17], v[106:107], v[40:41]
	v_cvt_pk_bf16_f32 v33, v28, v29
	v_pk_mul_f32 v[28:29], v[92:93], v[16:17]
	v_pk_fma_f32 v[16:17], v[16:17], v[98:99], v[42:43]
	v_cvt_pk_bf16_f32 v28, v28, v29
	v_pk_mul_f32 v[26:27], v[26:27], v[16:17]
	s_nop 0
	v_cvt_pk_bf16_f32 v26, v26, v27
	global_store_dword v[10:11], v0, off
	global_store_dword v[12:13], v108, off
	global_store_dword v[14:15], v109, off
	global_store_dword v[18:19], v46, off
	global_store_dword v[20:21], v47, off
	global_store_dword v[22:23], v48, off
	global_store_dword v[24:25], v49, off
	global_store_dword v[30:31], v50, off
	global_store_dword v[34:35], v51, off
	global_store_dword v[70:71], v52, off
	global_store_dword v[74:75], v44, off
	global_store_dword v[86:87], v45, off
	global_store_dword v[90:91], v32, off
	global_store_dword v[94:95], v33, off
	global_store_dword v[96:97], v28, off
	global_store_dword v[8:9], v26, off
	v_lshl_add_u64 v[8:9], v[8:9], 0, s[58:59]
	s_cbranch_scc0 .LBB0_492
	v_add_u32_e32 v36, s52, v36
	v_cmp_lt_i32_e32 vcc, s31, v36
	s_or_b64 s[34:35], vcc, s[34:35]
	v_add_u32_e32 v37, s8, v37
	s_andn2_b64 exec, exec, s[34:35]
	s_cbranch_execnz .LBB0_491

.LBB0_631:
	s_add_i32 s10, s11, 1
	s_cmp_gt_i32 s11, s1
	s_cbranch_scc1 .Lattn1_stage_only
	v_add3_u32 v0, s100, v180, v229
	ds_read_b128 v[2:5], v0
	ds_read_b128 v[6:9], v0 offset:32
	ds_read_b128 v[10:13], v0 offset:64
	ds_read_b128 v[184:187], v0 offset:96
	ds_read_b128 v[188:191], v0 offset:128
	ds_read_b128 v[192:195], v0 offset:160
	ds_read_b128 v[196:199], v0 offset:192
	s_mov_b32 s16, s101
	v_add_u32_e32 v247, s16, v233
	v_add_u32_e32 v248, s16, v234
	v_add_u32_e32 v249, s16, v236
	v_add_u32_e32 v250, s16, v208
	v_add_u32_e32 v251, s16, v200
	s_cmp_lt_u32 s11, s7
	s_cselect_b64 s[16:17], -1, 0
	s_cmp_lg_u64 s[16:17], 0
	s_addc_u32 s6, s6, 0
	s_mov_b32 s22, s14
	s_mov_b32 s23, s15
	s_mov_b32 s26, s14
	s_mov_b32 s27, s15
	v_mov_b32_e32 v80, v213
	v_mov_b32_e32 v81, v80
	v_mov_b32_e32 v82, v80
	v_mov_b32_e32 v83, v80
	v_mov_b32_e32 v84, v80
	v_mov_b32_e32 v85, v80
	v_mov_b32_e32 v86, v80
	v_mov_b32_e32 v87, v80
	v_mov_b32_e32 v88, v80
	v_mov_b32_e32 v89, v80
	v_mov_b32_e32 v90, v80
	v_mov_b32_e32 v91, v80
	v_mov_b32_e32 v92, v80
	v_mov_b32_e32 v93, v80
	v_mov_b32_e32 v94, v80
	v_mov_b32_e32 v95, v80
	s_mov_b32 s11, s100
	s_waitcnt lgkmcnt(6)
	v_mfma_f32_32x32x16_bf16 v[96:111], v[2:5], v[132:135], v[80:95]
	s_mul_i32 s16, s6, 0x6000
	s_waitcnt vmcnt(4)
	ds_write_b128 v247, v[112:115]
	buffer_load_dwordx4 v[112:115], v230, s[20:23], s16 offen
	ds_read_b128 v[2:5], v0 offset:224
	s_waitcnt lgkmcnt(6)
	v_mfma_f32_32x32x16_bf16 v[96:111], v[6:9], v[136:139], v[96:111]
	ds_read_b128 v[6:9], v0 offset:256
	s_waitcnt lgkmcnt(6)
	v_mfma_f32_32x32x16_bf16 v[96:111], v[10:13], v[140:143], v[96:111]
	s_add_i32 s17, s16, 0x2000
	s_waitcnt vmcnt(4)
	ds_write_b128 v248, v[116:119]
	buffer_load_dwordx4 v[116:119], v230, s[20:23], s17 offen
	ds_read_b128 v[10:13], v0 offset:288
	s_waitcnt lgkmcnt(6)
	v_mfma_f32_32x32x16_bf16 v[96:111], v[184:187], v[144:147], v[96:111]
	ds_read_b128 v[184:187], v0 offset:320
	s_waitcnt lgkmcnt(6)
	v_mfma_f32_32x32x16_bf16 v[96:111], v[188:191], v[152:155], v[96:111]
	s_addk_i32 s16, 0x4000
	s_waitcnt vmcnt(4)
	ds_write_b128 v249, v[120:123]
	buffer_load_dwordx4 v[120:123], v230, s[20:23], s16 offen
	ds_read_b128 v[188:191], v0 offset:352
	s_waitcnt lgkmcnt(6)
	v_mfma_f32_32x32x16_bf16 v[96:111], v[192:195], v[164:167], v[96:111]
	ds_read_b128 v[192:195], v0 offset:12800
	s_waitcnt lgkmcnt(6)
	v_mfma_f32_32x32x16_bf16 v[96:111], v[196:199], v[172:175], v[96:111]
	s_lshl_b32 s16, s6, 7
	s_waitcnt vmcnt(4)
	ds_write_b128 v250, v[124:127] offset:25600
	buffer_load_dwordx4 v[124:127], v232, s[24:27], s16 offen
	ds_read_b128 v[196:199], v0 offset:12832
	s_waitcnt lgkmcnt(6)
	v_mfma_f32_32x32x16_bf16 v[96:111], v[2:5], v[160:163], v[96:111]
	ds_read_b128 v[2:5], v0 offset:12864
	s_waitcnt lgkmcnt(6)
	v_mfma_f32_32x32x16_bf16 v[96:111], v[6:9], v[148:151], v[96:111]
	s_add_i32 s16, s16, 0x100000
	s_waitcnt vmcnt(4)
	ds_write_b128 v251, v[128:131] offset:25600
	buffer_load_dwordx4 v[128:131], v232, s[24:27], s16 offen
	ds_read_b128 v[6:9], v0 offset:12896
	s_waitcnt lgkmcnt(6)
	v_mfma_f32_32x32x16_bf16 v[96:111], v[10:13], v[168:171], v[96:111]
	ds_read_b128 v[10:13], v0 offset:12928
	s_waitcnt lgkmcnt(6)
	v_mfma_f32_32x32x16_bf16 v[96:111], v[184:187], v[156:159], v[96:111]
	ds_read_b128 v[184:187], v0 offset:12960
	s_waitcnt lgkmcnt(6)
	v_mfma_f32_32x32x16_bf16 v[96:111], v[188:191], v[176:179], v[96:111]
	ds_read_b128 v[188:191], v0 offset:12992
	s_waitcnt lgkmcnt(6)
	v_mfma_f32_32x32x16_bf16 v[80:95], v[192:195], v[132:135], v[80:95]
	s_nop 8
	v_exp_f32_e32 v206, v96
	v_exp_f32_e32 v207, v97
	ds_read_b128 v[192:195], v0 offset:13024
	s_waitcnt lgkmcnt(6)
	v_mfma_f32_32x32x16_bf16 v[80:95], v[196:199], v[136:139], v[80:95]
	v_add_f32_e32 v14, v207, v206
	v_add_f32_e32 v96, v182, v14
	ds_read_b128 v[196:199], v0 offset:13056
	s_waitcnt lgkmcnt(6)
	v_mfma_f32_32x32x16_bf16 v[80:95], v[2:5], v[140:143], v[80:95]
	v_exp_f32_e32 v15, v98
	v_exp_f32_e32 v183, v99
	v_exp_f32_e32 v14, v100
	v_exp_f32_e32 v182, v101
	ds_read_b128 v[2:5], v0 offset:13088
	s_waitcnt lgkmcnt(6)
	v_mfma_f32_32x32x16_bf16 v[80:95], v[6:9], v[144:147], v[80:95]
	v_add_f32_e64 v6, v182, v14
	v_add_f32_e64 v7, v183, v15
	v_add_f32_e32 v7, v7, v96
	v_add_f32_e32 v98, v6, v7
	ds_read_b128 v[6:9], v0 offset:13120
	s_waitcnt lgkmcnt(6)
	v_mfma_f32_32x32x16_bf16 v[80:95], v[10:13], v[152:155], v[80:95]
	v_exp_f32_e32 v203, v102
	v_exp_f32_e32 v205, v103
	v_exp_f32_e32 v202, v104
	v_exp_f32_e32 v204, v105
	ds_read_b128 v[10:13], v0 offset:13152
	s_waitcnt lgkmcnt(6)
	v_mfma_f32_32x32x16_bf16 v[80:95], v[184:187], v[164:167], v[80:95]
	v_add_f32_e64 v96, v204, v202
	v_add_f32_e64 v97, v205, v203
	v_add_f32_e32 v0, v97, v98
	v_add_f32_e32 v0, v96, v0
	v_add3_u32 v209, s11, v181, v229
	ds_read_b128 v[96:99], v209 offset:25600
	s_waitcnt lgkmcnt(6)
	v_mfma_f32_32x32x16_bf16 v[80:95], v[188:191], v[172:175], v[80:95]
	v_exp_f32_e32 v187, v106
	v_exp_f32_e32 v189, v107
	v_exp_f32_e32 v186, v108
	v_exp_f32_e32 v188, v109
	ds_read_b128 v[100:103], v209 offset:30208
	s_waitcnt lgkmcnt(6)
	v_mfma_f32_32x32x16_bf16 v[80:95], v[192:195], v[160:163], v[80:95]
	v_add_f32_e64 v104, v188, v186
	v_add_f32_e64 v105, v189, v187
	v_add_f32_e32 v0, v105, v0
	v_add_f32_e32 v190, v104, v0
	ds_read_b128 v[104:107], v209 offset:34816
	s_waitcnt lgkmcnt(6)
	v_mfma_f32_32x32x16_bf16 v[80:95], v[196:199], v[148:151], v[80:95]
	v_exp_f32_e32 v192, v110
	v_exp_f32_e32 v194, v111
	ds_read_b128 v[108:111], v209 offset:39424
	s_waitcnt lgkmcnt(6)
	v_mfma_f32_32x32x16_bf16 v[80:95], v[2:5], v[168:171], v[80:95]
	v_cvt_pk_bf16_f32 v2, v206, v207
	v_cvt_pk_bf16_f32 v3, v15, v183
	v_cvt_pk_bf16_f32 v4, v14, v182
	v_cvt_pk_bf16_f32 v5, v203, v205
	ds_read_b128 v[182:185], v209 offset:25632
	s_waitcnt lgkmcnt(6)
	v_mfma_f32_32x32x16_bf16 v[80:95], v[6:9], v[156:159], v[80:95]
	v_cvt_pk_bf16_f32 v6, v202, v204
	v_cvt_pk_bf16_f32 v7, v187, v189
	v_cvt_pk_bf16_f32 v8, v186, v188
	ds_read_b128 v[186:189], v209 offset:30240
	s_waitcnt lgkmcnt(6)
	v_mfma_f32_32x32x16_bf16 v[80:95], v[10:13], v[176:179], v[80:95]
	s_waitcnt lgkmcnt(5)
	v_mfma_f32_32x32x16_bf16 v[64:79], v[96:99], v[2:5], v[64:79]
	ds_read_b128 v[10:13], v209 offset:34848
	s_waitcnt lgkmcnt(5)
	v_mfma_f32_32x32x16_bf16 v[48:63], v[100:103], v[2:5], v[48:63]
	s_nop 6
	v_exp_f32_e32 v195, v80
	v_exp_f32_e32 v193, v81
	ds_read_b128 v[96:99], v209 offset:39456
	v_exp_f32_e32 v191, v82
	v_cvt_pk_bf16_f32 v9, v192, v194
	v_add_f32_e32 v14, v194, v192
	v_add_f32_e32 v15, v195, v193
	s_nop 0
	v_add_f32_e32 v14, v190, v14
	v_add_f32_e32 v15, v191, v15
	s_waitcnt lgkmcnt(5)
	v_mfma_f32_32x32x16_bf16 v[32:47], v[104:107], v[2:5], v[32:47]
	ds_read_b128 v[100:103], v209 offset:25664
	v_exp_f32_e32 v0, v83
	v_exp_f32_e32 v190, v84
	v_exp_f32_e32 v105, v85
	v_add_f32_e32 v107, v0, v190
	s_waitcnt lgkmcnt(5)
	v_mfma_f32_32x32x16_bf16 v[16:31], v[108:111], v[2:5], v[16:31]
	ds_read_b128 v[80:83], v209 offset:30272
	v_exp_f32_e32 v106, v86
	v_exp_f32_e32 v104, v87
	s_nop 0
	v_add_f32_e32 v108, v104, v106
	v_add_f32_e32 v109, v105, v107
	s_waitcnt lgkmcnt(5)
	v_mfma_f32_32x32x16_bf16 v[64:79], v[182:185], v[6:9], v[64:79]
	ds_read_b128 v[2:5], v209 offset:34880
	v_exp_f32_e32 v111, v88
	v_exp_f32_e32 v185, v89
	s_waitcnt lgkmcnt(5)
	v_mfma_f32_32x32x16_bf16 v[48:63], v[186:189], v[6:9], v[48:63]
	v_exp_f32_e32 v110, v90
	v_exp_f32_e32 v184, v91
	ds_read_b128 v[84:87], v209 offset:39488
	v_add_f32_e32 v182, v184, v110
	v_add_f32_e32 v183, v185, v111
	s_waitcnt lgkmcnt(5)
	v_mfma_f32_32x32x16_bf16 v[32:47], v[10:13], v[6:9], v[32:47]
	s_barrier
	ds_read_b128 v[88:91], v209 offset:25696
	v_exp_f32_e32 v187, v92
	v_exp_f32_e32 v189, v93
	s_waitcnt lgkmcnt(5)
	v_mfma_f32_32x32x16_bf16 v[16:31], v[96:99], v[6:9], v[16:31]
	v_exp_f32_e32 v186, v94
	v_exp_f32_e32 v188, v95
	v_add_f32_e32 v92, v14, v15
	v_add_f32_e32 v92, v109, v92
	v_add_f32_e32 v6, v108, v92
	ds_read_b128 v[10:13], v209 offset:30304
	v_add_f32_e32 v6, v183, v6
	v_add_f32_e32 v14, v188, v186
	v_add_f32_e32 v15, v189, v187
	v_add_f32_e32 v6, v182, v6
	v_add_f32_e32 v6, v15, v6
	v_add_f32_e32 v182, v14, v6
	v_cvt_pk_bf16_f32 v6, v195, v193
	v_cvt_pk_bf16_f32 v7, v191, v0
	v_cvt_pk_bf16_f32 v8, v190, v105
	v_cvt_pk_bf16_f32 v9, v106, v104
	v_cvt_pk_bf16_f32 v92, v111, v185
	v_cvt_pk_bf16_f32 v93, v110, v184
	v_cvt_pk_bf16_f32 v94, v187, v189
	v_cvt_pk_bf16_f32 v95, v186, v188
	s_waitcnt lgkmcnt(5)
	v_mfma_f32_32x32x16_bf16 v[64:79], v[100:103], v[6:9], v[64:79]
	ds_read_b128 v[96:99], v209 offset:34912
	s_waitcnt lgkmcnt(5)
	v_mfma_f32_32x32x16_bf16 v[48:63], v[80:83], v[6:9], v[48:63]
	ds_read_b128 v[100:103], v209 offset:39520
	s_waitcnt lgkmcnt(5)
	v_mfma_f32_32x32x16_bf16 v[32:47], v[2:5], v[6:9], v[32:47]
	s_waitcnt lgkmcnt(4)
	v_mfma_f32_32x32x16_bf16 v[16:31], v[84:87], v[6:9], v[16:31]
	s_waitcnt lgkmcnt(3)
	v_mfma_f32_32x32x16_bf16 v[64:79], v[88:91], v[92:95], v[64:79]
	s_waitcnt lgkmcnt(2)
	v_mfma_f32_32x32x16_bf16 v[48:63], v[10:13], v[92:95], v[48:63]
	s_waitcnt lgkmcnt(1)
	v_mfma_f32_32x32x16_bf16 v[32:47], v[96:99], v[92:95], v[32:47]
	s_waitcnt lgkmcnt(0)
	v_mfma_f32_32x32x16_bf16 v[16:31], v[100:103], v[92:95], v[16:31]

.LBB0_709:
	s_add_i32 s9, s10, 1
	s_cmp_gt_i32 s10, s1
	s_cbranch_scc1 .Lattn2_stage_only
	v_add3_u32 v0, s100, v180, v206
	ds_read_b128 v[2:5], v0
	ds_read_b128 v[6:9], v0 offset:32
	ds_read_b128 v[10:13], v0 offset:64
	ds_read_b128 v[184:187], v0 offset:96
	ds_read_b128 v[188:191], v0 offset:128
	ds_read_b128 v[192:195], v0 offset:160
	ds_read_b128 v[196:199], v0 offset:192
	s_mov_b32 s11, s101
	v_add_u32_e32 v247, s11, v227
	v_add_u32_e32 v248, s11, v228
	v_add_u32_e32 v249, s11, v229
	v_add_u32_e32 v250, s11, v200
	v_add_u32_e32 v251, s11, v202
	s_cmp_lt_u32 s10, s7
	s_cselect_b64 s[16:17], -1, 0
	s_cmp_lg_u64 s[16:17], 0
	s_addc_u32 s6, s6, 0
	s_mov_b32 s22, s14
	s_mov_b32 s23, s15
	s_mov_b32 s26, s14
	s_mov_b32 s27, s15
	v_mov_b32_e32 v80, v213
	v_mov_b32_e32 v81, v80
	v_mov_b32_e32 v82, v80
	v_mov_b32_e32 v83, v80
	v_mov_b32_e32 v84, v80
	v_mov_b32_e32 v85, v80
	v_mov_b32_e32 v86, v80
	v_mov_b32_e32 v87, v80
	v_mov_b32_e32 v88, v80
	v_mov_b32_e32 v89, v80
	v_mov_b32_e32 v90, v80
	v_mov_b32_e32 v91, v80
	v_mov_b32_e32 v92, v80
	v_mov_b32_e32 v93, v80
	v_mov_b32_e32 v94, v80
	v_mov_b32_e32 v95, v80
	s_mov_b32 s10, s100
	s_waitcnt lgkmcnt(6)
	v_mfma_f32_32x32x16_bf16 v[96:111], v[2:5], v[132:135], v[80:95]
	s_mul_i32 s11, s6, 0x6000
	s_waitcnt vmcnt(4)
	ds_write_b128 v247, v[112:115]
	buffer_load_dwordx4 v[112:115], v207, s[20:23], s11 offen
	ds_read_b128 v[2:5], v0 offset:224
	s_waitcnt lgkmcnt(6)
	v_mfma_f32_32x32x16_bf16 v[96:111], v[6:9], v[136:139], v[96:111]
	ds_read_b128 v[6:9], v0 offset:256
	s_waitcnt lgkmcnt(6)
	v_mfma_f32_32x32x16_bf16 v[96:111], v[10:13], v[140:143], v[96:111]
	s_add_i32 s16, s11, 0x2000
	s_waitcnt vmcnt(4)
	ds_write_b128 v248, v[116:119]
	buffer_load_dwordx4 v[116:119], v207, s[20:23], s16 offen
	ds_read_b128 v[10:13], v0 offset:288
	s_waitcnt lgkmcnt(6)
	v_mfma_f32_32x32x16_bf16 v[96:111], v[184:187], v[144:147], v[96:111]
	ds_read_b128 v[184:187], v0 offset:320
	s_waitcnt lgkmcnt(6)
	v_mfma_f32_32x32x16_bf16 v[96:111], v[188:191], v[148:151], v[96:111]
	s_addk_i32 s11, 0x4000
	s_waitcnt vmcnt(4)
	ds_write_b128 v249, v[120:123]
	buffer_load_dwordx4 v[120:123], v207, s[20:23], s11 offen
	ds_read_b128 v[188:191], v0 offset:352
	s_waitcnt lgkmcnt(6)
	v_mfma_f32_32x32x16_bf16 v[96:111], v[192:195], v[152:155], v[96:111]
	ds_read_b128 v[192:195], v0 offset:12800
	s_waitcnt lgkmcnt(6)
	v_mfma_f32_32x32x16_bf16 v[96:111], v[196:199], v[156:159], v[96:111]
	s_lshl_b32 s11, s6, 7
	s_waitcnt vmcnt(4)
	ds_write_b128 v250, v[124:127] offset:25600
	buffer_load_dwordx4 v[124:127], v209, s[24:27], s11 offen
	ds_read_b128 v[196:199], v0 offset:12832
	s_waitcnt lgkmcnt(6)
	v_mfma_f32_32x32x16_bf16 v[96:111], v[2:5], v[160:163], v[96:111]
	ds_read_b128 v[2:5], v0 offset:12864
	s_waitcnt lgkmcnt(6)
	v_mfma_f32_32x32x16_bf16 v[96:111], v[6:9], v[164:167], v[96:111]
	s_add_i32 s11, s11, 0x100000
	s_waitcnt vmcnt(4)
	ds_write_b128 v251, v[128:131] offset:25600
	buffer_load_dwordx4 v[128:131], v209, s[24:27], s11 offen
	ds_read_b128 v[6:9], v0 offset:12896
	s_waitcnt lgkmcnt(6)
	v_mfma_f32_32x32x16_bf16 v[96:111], v[10:13], v[172:175], v[96:111]
	ds_read_b128 v[10:13], v0 offset:12928
	s_waitcnt lgkmcnt(6)
	v_mfma_f32_32x32x16_bf16 v[96:111], v[184:187], v[168:171], v[96:111]
	ds_read_b128 v[184:187], v0 offset:12960
	s_waitcnt lgkmcnt(6)
	v_mfma_f32_32x32x16_bf16 v[96:111], v[188:191], v[176:179], v[96:111]
	ds_read_b128 v[188:191], v0 offset:12992
	s_waitcnt lgkmcnt(6)
	v_mfma_f32_32x32x16_bf16 v[80:95], v[192:195], v[132:135], v[80:95]
	s_nop 8
	v_exp_f32_e32 v203, v96
	v_exp_f32_e32 v208, v97
	ds_read_b128 v[192:195], v0 offset:13024
	s_waitcnt lgkmcnt(6)
	v_mfma_f32_32x32x16_bf16 v[80:95], v[196:199], v[136:139], v[80:95]
	v_add_f32_e32 v14, v208, v203
	v_add_f32_e32 v96, v182, v14
	ds_read_b128 v[196:199], v0 offset:13056
	s_waitcnt lgkmcnt(6)
	v_mfma_f32_32x32x16_bf16 v[80:95], v[2:5], v[140:143], v[80:95]
	v_exp_f32_e32 v15, v98
	v_exp_f32_e32 v183, v99
	v_exp_f32_e32 v14, v100
	v_exp_f32_e32 v182, v101
	ds_read_b128 v[2:5], v0 offset:13088
	s_waitcnt lgkmcnt(6)
	v_mfma_f32_32x32x16_bf16 v[80:95], v[6:9], v[144:147], v[80:95]
	v_add_f32_e64 v6, v182, v14
	v_add_f32_e64 v7, v183, v15
	v_add_f32_e32 v7, v7, v96
	v_add_f32_e32 v98, v6, v7
	ds_read_b128 v[6:9], v0 offset:13120
	s_waitcnt lgkmcnt(6)
	v_mfma_f32_32x32x16_bf16 v[80:95], v[10:13], v[148:151], v[80:95]
	v_exp_f32_e32 v231, v102
	v_exp_f32_e32 v233, v103
	v_exp_f32_e32 v230, v104
	v_exp_f32_e32 v232, v105
	ds_read_b128 v[10:13], v0 offset:13152
	s_waitcnt lgkmcnt(6)
	v_mfma_f32_32x32x16_bf16 v[80:95], v[184:187], v[152:155], v[80:95]
	v_add_f32_e64 v96, v232, v230
	v_add_f32_e64 v97, v233, v231
	v_add_f32_e32 v0, v97, v98
	v_add_f32_e32 v0, v96, v0
	v_add3_u32 v234, s10, v181, v206
	ds_read_b128 v[96:99], v234 offset:25600
	s_waitcnt lgkmcnt(6)
	v_mfma_f32_32x32x16_bf16 v[80:95], v[188:191], v[156:159], v[80:95]
	v_exp_f32_e32 v187, v106
	v_exp_f32_e32 v189, v107
	v_exp_f32_e32 v186, v108
	v_exp_f32_e32 v188, v109
	ds_read_b128 v[100:103], v234 offset:30208
	s_waitcnt lgkmcnt(6)
	v_mfma_f32_32x32x16_bf16 v[80:95], v[192:195], v[160:163], v[80:95]
	v_add_f32_e64 v104, v188, v186
	v_add_f32_e64 v105, v189, v187
	v_add_f32_e32 v0, v105, v0
	v_add_f32_e32 v190, v104, v0
	ds_read_b128 v[104:107], v234 offset:34816
	s_waitcnt lgkmcnt(6)
	v_mfma_f32_32x32x16_bf16 v[80:95], v[196:199], v[164:167], v[80:95]
	v_exp_f32_e32 v192, v110
	v_exp_f32_e32 v194, v111
	ds_read_b128 v[108:111], v234 offset:39424
	s_waitcnt lgkmcnt(6)
	v_mfma_f32_32x32x16_bf16 v[80:95], v[2:5], v[172:175], v[80:95]
	v_cvt_pk_bf16_f32 v2, v203, v208
	v_cvt_pk_bf16_f32 v3, v15, v183
	v_cvt_pk_bf16_f32 v4, v14, v182
	v_cvt_pk_bf16_f32 v5, v231, v233
	ds_read_b128 v[182:185], v234 offset:25632
	s_waitcnt lgkmcnt(6)
	v_mfma_f32_32x32x16_bf16 v[80:95], v[6:9], v[168:171], v[80:95]
	v_cvt_pk_bf16_f32 v6, v230, v232
	v_cvt_pk_bf16_f32 v7, v187, v189
	v_cvt_pk_bf16_f32 v8, v186, v188
	ds_read_b128 v[186:189], v234 offset:30240
	s_waitcnt lgkmcnt(6)
	v_mfma_f32_32x32x16_bf16 v[80:95], v[10:13], v[176:179], v[80:95]
	s_waitcnt lgkmcnt(5)
	v_mfma_f32_32x32x16_bf16 v[64:79], v[96:99], v[2:5], v[64:79]
	ds_read_b128 v[10:13], v234 offset:34848
	s_waitcnt lgkmcnt(5)
	v_mfma_f32_32x32x16_bf16 v[48:63], v[100:103], v[2:5], v[48:63]
	s_nop 6
	v_exp_f32_e32 v195, v80
	v_exp_f32_e32 v193, v81
	ds_read_b128 v[96:99], v234 offset:39456
	v_exp_f32_e32 v191, v82
	v_cvt_pk_bf16_f32 v9, v192, v194
	v_add_f32_e32 v14, v194, v192
	v_add_f32_e32 v15, v195, v193
	s_nop 0
	v_add_f32_e32 v14, v190, v14
	v_add_f32_e32 v15, v191, v15
	s_waitcnt lgkmcnt(5)
	v_mfma_f32_32x32x16_bf16 v[32:47], v[104:107], v[2:5], v[32:47]
	ds_read_b128 v[100:103], v234 offset:25664
	v_exp_f32_e32 v0, v83
	v_exp_f32_e32 v190, v84
	v_exp_f32_e32 v105, v85
	v_add_f32_e32 v107, v0, v190
	s_waitcnt lgkmcnt(5)
	v_mfma_f32_32x32x16_bf16 v[16:31], v[108:111], v[2:5], v[16:31]
	ds_read_b128 v[80:83], v234 offset:30272
	v_exp_f32_e32 v106, v86
	v_exp_f32_e32 v104, v87
	s_nop 0
	v_add_f32_e32 v108, v104, v106
	v_add_f32_e32 v109, v105, v107
	s_waitcnt lgkmcnt(5)
	v_mfma_f32_32x32x16_bf16 v[64:79], v[182:185], v[6:9], v[64:79]
	ds_read_b128 v[2:5], v234 offset:34880
	v_exp_f32_e32 v111, v88
	v_exp_f32_e32 v185, v89
	s_waitcnt lgkmcnt(5)
	v_mfma_f32_32x32x16_bf16 v[48:63], v[186:189], v[6:9], v[48:63]
	v_exp_f32_e32 v110, v90
	v_exp_f32_e32 v184, v91
	ds_read_b128 v[84:87], v234 offset:39488
	v_add_f32_e32 v182, v184, v110
	v_add_f32_e32 v183, v185, v111
	s_waitcnt lgkmcnt(5)
	v_mfma_f32_32x32x16_bf16 v[32:47], v[10:13], v[6:9], v[32:47]
	s_barrier
	ds_read_b128 v[88:91], v234 offset:25696
	v_exp_f32_e32 v187, v92
	v_exp_f32_e32 v189, v93
	s_waitcnt lgkmcnt(5)
	v_mfma_f32_32x32x16_bf16 v[16:31], v[96:99], v[6:9], v[16:31]
	v_exp_f32_e32 v186, v94
	v_exp_f32_e32 v188, v95
	v_add_f32_e32 v92, v14, v15
	v_add_f32_e32 v92, v109, v92
	v_add_f32_e32 v6, v108, v92
	ds_read_b128 v[10:13], v234 offset:30304
	v_add_f32_e32 v6, v183, v6
	v_add_f32_e32 v14, v188, v186
	v_add_f32_e32 v15, v189, v187
	v_add_f32_e32 v6, v182, v6
	v_add_f32_e32 v6, v15, v6
	v_add_f32_e32 v182, v14, v6
	v_cvt_pk_bf16_f32 v6, v195, v193
	v_cvt_pk_bf16_f32 v7, v191, v0
	v_cvt_pk_bf16_f32 v8, v190, v105
	v_cvt_pk_bf16_f32 v9, v106, v104
	v_cvt_pk_bf16_f32 v92, v111, v185
	v_cvt_pk_bf16_f32 v93, v110, v184
	v_cvt_pk_bf16_f32 v94, v187, v189
	v_cvt_pk_bf16_f32 v95, v186, v188
	s_waitcnt lgkmcnt(5)
	v_mfma_f32_32x32x16_bf16 v[64:79], v[100:103], v[6:9], v[64:79]
	ds_read_b128 v[96:99], v234 offset:34912
	s_waitcnt lgkmcnt(5)
	v_mfma_f32_32x32x16_bf16 v[48:63], v[80:83], v[6:9], v[48:63]
	ds_read_b128 v[100:103], v234 offset:39520
	s_waitcnt lgkmcnt(5)
	v_mfma_f32_32x32x16_bf16 v[32:47], v[2:5], v[6:9], v[32:47]
	s_waitcnt lgkmcnt(4)
	v_mfma_f32_32x32x16_bf16 v[16:31], v[84:87], v[6:9], v[16:31]
	s_waitcnt lgkmcnt(3)
	v_mfma_f32_32x32x16_bf16 v[64:79], v[88:91], v[92:95], v[64:79]
	s_waitcnt lgkmcnt(2)
	v_mfma_f32_32x32x16_bf16 v[48:63], v[10:13], v[92:95], v[48:63]
	s_waitcnt lgkmcnt(1)
	v_mfma_f32_32x32x16_bf16 v[32:47], v[96:99], v[92:95], v[32:47]
	s_waitcnt lgkmcnt(0)
	v_mfma_f32_32x32x16_bf16 v[16:31], v[100:103], v[92:95], v[16:31]
